# code placement: the hand-written attention far-tile blocks (diff, diff-last, FoX) start on 64-byte boundaries (the diff block started at 4 mod 8 bytes)
# speedup vs baseline: 1.0037x; 1.0037x over previous
.LBB0_240:
	v_add_f32_e32 v120, s23, v120
	s_and_saveexec_b64 s[14:15], s[0:1]
	s_cbranch_execz .LBB0_226
	s_add_i32 s22, s34, -1
	s_and_b32 s23, s22, 3
	s_lshl_b32 s23, s23, 2
	s_add_i32 s24, s23, 0
	v_fmamk_f32 v2, v120, 0x3fb8aa3b, v95
	s_cmp_le_i32 s22, s28
	s_waitcnt lgkmcnt(0)
	v_sub_f32_e32 v2, v2, v117
	s_mov_b32 s25, 0xc2000000
	s_cselect_b64 s[22:23], -1, 0
	v_cmp_gt_f32_e32 vcc, s25, v2
	s_and_b64 s[22:23], s[22:23], vcc
	v_cndmask_b32_e64 v2, 0, 1, s[22:23]
	v_mov_b32_e32 v3, s24
	ds_write_b32 v3, v2 offset:44672
	s_branch .LBB0_226
	.p2align 6

; #define LAS __attribute__((address_space(3)))
; #define MFMA32(a, b, c) __builtin_amdgcn_mfma_f32_32x32x16_bf16((a), (b), (c), 0, 0, 0)
; __device__ __forceinline__ int crow(int r, int hi) { return (r & 3) + 8 * (r >> 2) + 4 * hi; }
; template <int MODE>
; __device__ __forceinline__ void attn_item(const AttnP& p, int b, int h, int qb, LAS unsigned char* lds) {
;     ...
;                         if (qw - (kp0 + 31) >= 128) {
;                             const float cb = tab[255] - mfix;
; #pragma unroll
;                             for (int c = 0; c < NC; ++c) { ATT_QK(c, cb); ATT_TAIL(c); }
;                         } else {
;                             float binit[16];
; #pragma unroll
;                             for (int i = 0; i < 16; ++i) {
;                                 const int dist = qrow - (kp0 + crow(i, hh));
;                                 binit[i] = (dist < 0) ? -3e38f : (tab[dist > 255 ? 255 : dist] - mfix);
;                             }
; #pragma unroll
;                             for (int c = 0; c < NC; ++c) { ATT_QK(c, binit[i]); ATT_TAIL(c); }
;                         }
;                     } else {
;                         float binit[16];
;                         const LAS float* bl = (const LAS float*)(vtb + VT_BYTES) + 32 * kb2 + 4 * hh;
; #pragma unroll
;                         for (int g = 0; g < 4; ++g) {
;                             const f32x4 t = *(const LAS f32x4*)(bl + 8 * g);
; #pragma unroll
;                             for (int e = 0; e < 4; ++e) binit[4 * g + e] = (need_mask && (kp0 + crow(4 * g + e, hh) > qrow)) ? -3e38f : (t[e] - mfix);
;                         }
;                         ATT_QK(0, binit[i]); ATT_TAIL(0);
;                     }
;     ...
;                 }
; #pragma unroll
;                 for (int t2 = 0; t2 < 2; ++t2)
; #pragma unroll
;                     for (int d = 0; d < DV / 32; ++d) {
;                         const LAS unsigned char* vp = vtb + ((32 * kb2 + 16 * t2 + 4 * hh + ((lane & 15) >> 2)) * VPT + d * 32 + 16 * ((lane >> 4) & 1) + 4 * (lane & 3)) * 2;
;                         const s16x4 lo = vtr(vp), hi = vtr(vp + 8 * VPT * 2);
;                         const bf16x8 va = __builtin_shufflevector(lo, hi, 0, 1, 2, 3, 4, 5, 6, 7);
; #pragma unroll
;                         for (int c = 0; c < NC; ++c) O[c][d] = MFMA32(va, pb[c][t2], O[c][d]);
;                     }
.LBB0_575:
	s_waitcnt vmcnt(0) lgkmcnt(0)
	v_and_b32_e32 v135, 0xffff0000, v181
	v_and_b32_e32 v133, 0xffff0000, v180
	v_lshlrev_b32_e32 v134, 16, v181
	v_lshlrev_b32_e32 v132, 16, v180
	v_mov_b32_e32 v136, v135
	v_mov_b32_e32 v137, v133
	v_mov_b32_e32 v130, v134
	v_mov_b32_e32 v131, v132
	v_pk_mul_f32 v[136:137], v[136:137], v[136:137]
	v_and_b32_e32 v139, 0xffff0000, v178
	v_pk_fma_f32 v[130:131], v[130:131], v[130:131], v[136:137]
	v_and_b32_e32 v137, 0xffff0000, v179
	v_lshlrev_b32_e32 v136, 16, v179
	v_lshlrev_b32_e32 v138, 16, v178
	v_mov_b32_e32 v142, v139
	v_mov_b32_e32 v143, v137
	v_mov_b32_e32 v140, v138
	v_mov_b32_e32 v141, v136
	v_pk_mul_f32 v[142:143], v[142:143], v[142:143]
	s_xor_b32 s2, s5, 1
	v_pk_fma_f32 v[140:141], v[140:141], v[140:141], v[142:143]
	s_mul_i32 s2, s2, 0x9500
	v_add_f32_e32 v140, v140, v141
	v_add_f32_e32 v131, v131, v140
	v_add_f32_e32 v130, v130, v131
	s_add_i32 s2, s2, 0
	s_nop 0
	v_add_f32_dpp v130, v130, v130 quad_perm:[1,0,3,2] row_mask:0xf bank_mask:0xf bound_ctrl:1
	s_nop 1
	v_add_f32_dpp v130, v130, v130 quad_perm:[2,3,0,1] row_mask:0xf bank_mask:0xf bound_ctrl:1
	s_nop 1
	v_add_f32_dpp v130, v130, v130 row_half_mirror row_mask:0xf bank_mask:0xf bound_ctrl:1
	v_fmamk_f32 v130, v130, 0x3c800000, v211
	v_rsq_f32_e32 v140, v130
	s_nop 0
	v_pk_mul_f32 v[130:131], v[140:141], v[138:139] op_sel_hi:[0,1]
	v_pk_mul_f32 v[136:137], v[140:141], v[136:137] op_sel_hi:[0,1]
	v_pk_mul_f32 v[132:133], v[140:141], v[132:133] op_sel_hi:[0,1]
	v_pk_mul_f32 v[134:135], v[140:141], v[134:135] op_sel_hi:[0,1]
	v_cvt_pk_bf16_f32 v130, v130, v131
	v_cvt_pk_bf16_f32 v131, v136, v137
	v_cvt_pk_bf16_f32 v132, v132, v133
	v_cvt_pk_bf16_f32 v133, v134, v135
	v_add_u32_e32 v134, s2, v231
	ds_write_b128 v134, v[130:133]
	v_and_b32_e32 v135, 0xffff0000, v185
	v_and_b32_e32 v133, 0xffff0000, v184
	v_add_u32_e32 v130, s2, v232
	v_lshlrev_b32_e32 v134, 16, v185
	v_lshlrev_b32_e32 v132, 16, v184
	v_mov_b32_e32 v136, v135
	v_mov_b32_e32 v137, v133
	ds_write_b128 v130, v[186:189] offset:17408
	v_mov_b32_e32 v130, v134
	v_mov_b32_e32 v131, v132
	v_pk_mul_f32 v[136:137], v[136:137], v[136:137]
	v_and_b32_e32 v139, 0xffff0000, v182
	v_pk_fma_f32 v[130:131], v[130:131], v[130:131], v[136:137]
	v_and_b32_e32 v137, 0xffff0000, v183
	v_lshlrev_b32_e32 v136, 16, v183
	v_lshlrev_b32_e32 v138, 16, v182
	v_mov_b32_e32 v142, v139
	v_mov_b32_e32 v143, v137
	v_mov_b32_e32 v140, v138
	v_mov_b32_e32 v141, v136
	v_pk_mul_f32 v[142:143], v[142:143], v[142:143]
	s_nop 0
	v_pk_fma_f32 v[140:141], v[140:141], v[140:141], v[142:143]
	s_nop 0
	v_add_f32_e32 v140, v140, v141
	v_add_f32_e32 v131, v131, v140
	v_add_f32_e32 v130, v130, v131
	s_nop 1
	v_add_f32_dpp v130, v130, v130 quad_perm:[1,0,3,2] row_mask:0xf bank_mask:0xf bound_ctrl:1
	s_nop 1
	v_add_f32_dpp v130, v130, v130 quad_perm:[2,3,0,1] row_mask:0xf bank_mask:0xf bound_ctrl:1
	s_nop 1
	v_add_f32_dpp v130, v130, v130 row_half_mirror row_mask:0xf bank_mask:0xf bound_ctrl:1
	v_fmamk_f32 v130, v130, 0x3c800000, v211
	v_rsq_f32_e32 v140, v130
	s_nop 0
	v_pk_mul_f32 v[130:131], v[140:141], v[138:139] op_sel_hi:[0,1]
	v_pk_mul_f32 v[136:137], v[140:141], v[136:137] op_sel_hi:[0,1]
	v_pk_mul_f32 v[132:133], v[140:141], v[132:133] op_sel_hi:[0,1]
	v_pk_mul_f32 v[134:135], v[140:141], v[134:135] op_sel_hi:[0,1]
	v_cvt_pk_bf16_f32 v130, v130, v131
	v_cvt_pk_bf16_f32 v131, v136, v137
	v_cvt_pk_bf16_f32 v132, v132, v133
	v_cvt_pk_bf16_f32 v133, v134, v135
	v_add_u32_e32 v134, s2, v233
	ds_write_b128 v134, v[130:133]
	v_add_u32_e32 v130, s2, v234
	ds_write_b128 v130, v[190:193] offset:17408
	s_branch .LBB0_495
	.p2align 6
.Lfar_tile:
	s_andn2_b64 vcc, exec, s[6:7]
	s_cbranch_vccnz .Lfar_tile_last
	s_xor_b32 s2, s5, 1
	s_mul_i32 s2, s2, 0x9500
	v_add_u32_e32 v243, v242, v235
	ds_read_b128 v[244:247], v243 offset:8704
	ds_read_b128 v[248:251], v243 offset:8736
	ds_read_b128 v[194:197], v243 offset:8768
	ds_read_b128 v[198:201], v243 offset:8800
	ds_read_b128 v[202:205], v243 offset:8832
	ds_read_b128 v[214:217], v207 offset:4096
	v_add_u32_e32 v218, s15, v238
	v_add_u32_e32 v219, s15, v239
	s_waitcnt lgkmcnt(5)
	v_mfma_f32_32x32x16_bf16 v[146:161], v[244:247], v[162:165], 0
	s_waitcnt lgkmcnt(4)
	v_mfma_f32_32x32x16_bf16 v[146:161], v[248:251], v[166:169], v[146:161]
	ds_read_b128 v[244:247], v243 offset:8864
	ds_read_b128 v[248:251], v207 offset:5120
	s_waitcnt lgkmcnt(5)
	v_mfma_f32_32x32x16_bf16 v[146:161], v[194:197], v[170:173], v[146:161]
	s_waitcnt lgkmcnt(4)
	v_mfma_f32_32x32x16_bf16 v[146:161], v[198:201], v[174:177], v[146:161]
	ds_read_b128 v[194:197], v243 offset:8896
	ds_read_b128 v[198:201], v207 offset:6144
	s_waitcnt lgkmcnt(4)
	v_mfma_f32_32x32x16_bf16 v[130:145], v[202:205], v[214:217], 0
	ds_read_b128 v[202:205], v243 offset:8928
	ds_read_b128 v[214:217], v207 offset:7168
	s_waitcnt lgkmcnt(4)
	v_mfma_f32_32x32x16_bf16 v[130:145], v[244:247], v[248:251], v[130:145]
	ds_read_b64_tr_b16 v[244:245], v218 offset:17408
	ds_read_b64_tr_b16 v[246:247], v218 offset:19968
	ds_read_b64_tr_b16 v[248:249], v218 offset:17472
	ds_read_b64_tr_b16 v[250:251], v218 offset:20032
	v_exp_f32_e32 v146, v146
	v_exp_f32_e32 v147, v147
	v_exp_f32_e32 v148, v148
	v_add_f32_e32 v220, v146, v147
	v_exp_f32_e32 v149, v149
	v_add_f32_e32 v220, v148, v220
	v_exp_f32_e32 v150, v150
	s_waitcnt lgkmcnt(6)
	v_mfma_f32_32x32x16_bf16 v[130:145], v[194:197], v[198:201], v[130:145]
	ds_read_b64_tr_b16 v[194:195], v218 offset:17536
	ds_read_b64_tr_b16 v[196:197], v218 offset:20096
	ds_read_b64_tr_b16 v[198:199], v218 offset:17600
	ds_read_b64_tr_b16 v[200:201], v218 offset:20160
	v_add_f32_e32 v220, v149, v220
	v_exp_f32_e32 v151, v151
	v_add_f32_e32 v220, v150, v220
	v_exp_f32_e32 v152, v152
	v_add_f32_e32 v220, v151, v220
	v_exp_f32_e32 v153, v153
	s_waitcnt lgkmcnt(8)
; #define LAS __attribute__((address_space(3)))
; #define MFMA32(a, b, c) __builtin_amdgcn_mfma_f32_32x32x16_bf16((a), (b), (c), 0, 0, 0)
; template <int MODE>
; __device__ __forceinline__ void attn_item(const AttnP& p, int b, int h, int qb, LAS unsigned char* lds) {
;     ...
;                     if (MODE == 0) {
;                         const LAS float* tab = (const LAS float*)(lds + TAB_OFF);
;                         if (qw - (kp0 + 31) >= 128) {
;                             const float cb = tab[255] - mfix;
; #pragma unroll
;                             for (int c = 0; c < NC; ++c) { ATT_QK(c, cb); ATT_TAIL(c); }
;                         } else {
;                             float binit[16];
; #pragma unroll
;                             for (int i = 0; i < 16; ++i) {
;                                 const int dist = qrow - (kp0 + crow(i, hh));
;                                 binit[i] = (dist < 0) ? -3e38f : (tab[dist > 255 ? 255 : dist] - mfix);
;                             }
; #pragma unroll
;                             for (int c = 0; c < NC; ++c) { ATT_QK(c, binit[i]); ATT_TAIL(c); }
;                         }
;                     } else {
;                         float binit[16];
;                         const LAS float* bl = (const LAS float*)(vtb + VT_BYTES) + 32 * kb2 + 4 * hh;
; #pragma unroll
;                         for (int g = 0; g < 4; ++g) {
;                             const f32x4 t = *(const LAS f32x4*)(bl + 8 * g);
; #pragma unroll
;                             for (int e = 0; e < 4; ++e) binit[4 * g + e] = (need_mask && (kp0 + crow(4 * g + e, hh) > qrow)) ? -3e38f : (t[e] - mfix);
;                         }
;                         ATT_QK(0, binit[i]); ATT_TAIL(0);
;                     }
;     ...
;                 }
; #pragma unroll
;                 for (int t2 = 0; t2 < 2; ++t2)
; #pragma unroll
;                     for (int d = 0; d < DV / 32; ++d) {
;                         const LAS unsigned char* vp = vtb + ((32 * kb2 + 16 * t2 + 4 * hh + ((lane & 15) >> 2)) * VPT + d * 32 + 16 * ((lane >> 4) & 1) + 4 * (lane & 3)) * 2;
;                         const s16x4 lo = vtr(vp), hi = vtr(vp + 8 * VPT * 2);
;                         const bf16x8 va = __builtin_shufflevector(lo, hi, 0, 1, 2, 3, 4, 5, 6, 7);
; #pragma unroll
;                         for (int c = 0; c < NC; ++c) O[c][d] = MFMA32(va, pb[c][t2], O[c][d]);
	v_mfma_f32_32x32x16_bf16 v[130:145], v[202:205], v[214:217], v[130:145]
	ds_read_b64_tr_b16 v[202:203], v219 offset:17408
	ds_read_b64_tr_b16 v[204:205], v219 offset:19968
	ds_read_b64_tr_b16 v[214:215], v219 offset:17472
	ds_read_b64_tr_b16 v[216:217], v219 offset:20032
	v_add_f32_e32 v220, v152, v220
	v_cvt_pk_bf16_f32 v146, v146, v147
	v_add_f32_e32 v220, v153, v220
	v_cvt_pk_bf16_f32 v147, v148, v149
	v_cvt_pk_bf16_f32 v148, v150, v151
	v_cvt_pk_bf16_f32 v149, v152, v153
	s_nop 1
	s_waitcnt lgkmcnt(10)
	v_mfma_f32_32x32x16_bf16 v[114:129], v[244:247], v[146:149], v[114:129]
	v_exp_f32_e32 v154, v154
	v_exp_f32_e32 v155, v155
	v_add_f32_e32 v220, v154, v220
	v_exp_f32_e32 v156, v156
	v_add_f32_e32 v220, v155, v220
	v_exp_f32_e32 v157, v157
	s_waitcnt lgkmcnt(8)
	v_mfma_f32_32x32x16_bf16 v[82:97], v[248:251], v[146:149], v[82:97]
	v_add_f32_e32 v220, v156, v220
	v_exp_f32_e32 v158, v158
	v_add_f32_e32 v220, v157, v220
	v_exp_f32_e32 v159, v159
	v_add_f32_e32 v220, v158, v220
	s_waitcnt lgkmcnt(6)
	v_mfma_f32_32x32x16_bf16 v[50:65], v[194:197], v[146:149], v[50:65]
	v_exp_f32_e32 v160, v160
	v_add_f32_e32 v220, v159, v220
	v_exp_f32_e32 v161, v161
	v_add_f32_e32 v220, v160, v220
	v_cvt_pk_bf16_f32 v150, v154, v155
	s_waitcnt lgkmcnt(4)
	v_mfma_f32_32x32x16_bf16 v[34:49], v[198:201], v[146:149], v[34:49]
	v_add_f32_e32 v220, v161, v220
	v_cvt_pk_bf16_f32 v151, v156, v157
	v_cvt_pk_bf16_f32 v152, v158, v159
	v_cvt_pk_bf16_f32 v153, v160, v161
	v_add_f32_e32 v209, v209, v220
	ds_read_b64_tr_b16 v[154:155], v219 offset:17536
	ds_read_b64_tr_b16 v[156:157], v219 offset:20096
	ds_read_b64_tr_b16 v[158:159], v219 offset:17600
	ds_read_b64_tr_b16 v[160:161], v219 offset:20160
	s_waitcnt lgkmcnt(6)
	v_mfma_f32_32x32x16_bf16 v[114:129], v[202:205], v[150:153], v[114:129]
	v_exp_f32_e32 v130, v130
	v_exp_f32_e32 v131, v131
	v_exp_f32_e32 v132, v132
	v_add_f32_e32 v213, v130, v131
	v_exp_f32_e32 v133, v133
	s_waitcnt lgkmcnt(4)
	v_mfma_f32_32x32x16_bf16 v[82:97], v[214:217], v[150:153], v[82:97]
	v_add_f32_e32 v213, v132, v213
	v_exp_f32_e32 v134, v134
	v_add_f32_e32 v213, v133, v213
	v_exp_f32_e32 v135, v135
	v_add_f32_e32 v213, v134, v213
	s_waitcnt lgkmcnt(2)
	v_mfma_f32_32x32x16_bf16 v[50:65], v[154:157], v[150:153], v[50:65]
	v_exp_f32_e32 v136, v136
	v_add_f32_e32 v213, v135, v213
	v_exp_f32_e32 v137, v137
	v_add_f32_e32 v213, v136, v213
	v_cvt_pk_bf16_f32 v130, v130, v131
	s_waitcnt lgkmcnt(0)
	v_mfma_f32_32x32x16_bf16 v[34:49], v[158:161], v[150:153], v[34:49]
	v_add_f32_e32 v213, v137, v213
	v_cvt_pk_bf16_f32 v131, v132, v133
	v_cvt_pk_bf16_f32 v132, v134, v135
	v_cvt_pk_bf16_f32 v133, v136, v137
	s_nop 1
	v_mfma_f32_32x32x16_bf16 v[98:113], v[244:247], v[130:133], v[98:113]
	v_exp_f32_e32 v138, v138
	v_exp_f32_e32 v139, v139
	v_add_f32_e32 v213, v138, v213
	v_exp_f32_e32 v140, v140
	v_add_f32_e32 v213, v139, v213
	v_exp_f32_e32 v141, v141
	ds_read_b128 v[244:247], v243 offset:0
	v_mfma_f32_32x32x16_bf16 v[66:81], v[248:251], v[130:133], v[66:81]
	v_add_f32_e32 v213, v140, v213
	v_exp_f32_e32 v142, v142
	v_add_f32_e32 v213, v141, v213
	v_exp_f32_e32 v143, v143
	v_add_f32_e32 v213, v142, v213
	ds_read_b128 v[248:251], v243 offset:32
	v_mfma_f32_32x32x16_bf16 v[18:33], v[194:197], v[130:133], v[18:33]
	v_exp_f32_e32 v144, v144
	v_add_f32_e32 v213, v143, v213
	v_exp_f32_e32 v145, v145
	v_add_f32_e32 v213, v144, v213
	v_cvt_pk_bf16_f32 v134, v138, v139
	ds_read_b128 v[194:197], v243 offset:64
	v_mfma_f32_32x32x16_bf16 v[2:17], v[198:201], v[130:133], v[2:17]
	v_add_f32_e32 v213, v145, v213
	v_cvt_pk_bf16_f32 v135, v140, v141
	v_cvt_pk_bf16_f32 v136, v142, v143
	v_cvt_pk_bf16_f32 v137, v144, v145
	v_add_f32_e32 v208, v208, v213
	ds_read_b128 v[198:201], v243 offset:96
	s_nop 1
	v_mfma_f32_32x32x16_bf16 v[98:113], v[202:205], v[134:137], v[98:113]
	s_waitcnt vmcnt(3)
	v_and_b32_e32 v138, 0xffff0000, v181
	v_lshlrev_b32_e32 v142, 16, v181
	v_mul_f32_e32 v138, v138, v138
	v_fmac_f32_e32 v138, v142, v142
	v_and_b32_e32 v139, 0xffff0000, v180
	ds_read_b128 v[202:205], v243 offset:128
	v_mfma_f32_32x32x16_bf16 v[66:81], v[214:217], v[134:137], v[66:81]
	v_lshlrev_b32_e32 v142, 16, v180
	v_mul_f32_e32 v139, v139, v139
	v_fmac_f32_e32 v139, v142, v142
	v_and_b32_e32 v140, 0xffff0000, v178
	v_lshlrev_b32_e32 v142, 16, v178
	v_mul_f32_e32 v140, v140, v140
	ds_read_b128 v[214:217], v207 offset:4096
	v_mfma_f32_32x32x16_bf16 v[18:33], v[154:157], v[134:137], v[18:33]
	v_fmac_f32_e32 v140, v142, v142
	v_and_b32_e32 v141, 0xffff0000, v179
	v_lshlrev_b32_e32 v142, 16, v179
	v_mul_f32_e32 v141, v141, v141
	v_fmac_f32_e32 v141, v142, v142
	v_add_f32_e32 v140, v140, v141
	v_mfma_f32_32x32x16_bf16 v[2:17], v[158:161], v[134:137], v[2:17]
	v_add_f32_e32 v139, v139, v140
	v_add_f32_e32 v138, v138, v139
	s_nop 1
	v_add_f32_dpp v138, v138, v138 quad_perm:[1,0,3,2] row_mask:0xf bank_mask:0xf bound_ctrl:1
	s_nop 1
	v_add_f32_dpp v138, v138, v138 quad_perm:[2,3,0,1] row_mask:0xf bank_mask:0xf bound_ctrl:1
	v_add_u32_e32 v218, s15, v237
	v_add_u32_e32 v219, s15, v240
	s_waitcnt lgkmcnt(5)
	v_mfma_f32_32x32x16_bf16 v[146:161], v[244:247], v[162:165], 0
	s_nop 1
	v_add_f32_dpp v138, v138, v138 row_half_mirror row_mask:0xf bank_mask:0xf bound_ctrl:1
	v_fmamk_f32 v138, v138, 0x3c800000, v211
	v_rsq_f32_e32 v138, v138
	v_lshlrev_b32_e32 v139, 16, v178
	v_and_b32_e32 v140, 0xffff0000, v178
	s_waitcnt lgkmcnt(4)
	v_mfma_f32_32x32x16_bf16 v[146:161], v[248:251], v[166:169], v[146:161]
	v_mul_f32_e32 v139, v138, v139
	v_mul_f32_e32 v140, v138, v140
	v_cvt_pk_bf16_f32 v178, v139, v140
	v_lshlrev_b32_e32 v139, 16, v179
	v_and_b32_e32 v140, 0xffff0000, v179
	v_mul_f32_e32 v139, v138, v139
	ds_read_b128 v[244:247], v243 offset:160
	ds_read_b128 v[248:251], v207 offset:5120
	s_waitcnt lgkmcnt(5)
; #define LAS __attribute__((address_space(3)))
; #define MFMA32(a, b, c) __builtin_amdgcn_mfma_f32_32x32x16_bf16((a), (b), (c), 0, 0, 0)
; template <int MODE>
; __device__ __forceinline__ void attn_item(const AttnP& p, int b, int h, int qb, LAS unsigned char* lds) {
;     ...
;                     if (MODE == 0) {
;                         const LAS float* tab = (const LAS float*)(lds + TAB_OFF);
;                         if (qw - (kp0 + 31) >= 128) {
;                             const float cb = tab[255] - mfix;
; #pragma unroll
;                             for (int c = 0; c < NC; ++c) { ATT_QK(c, cb); ATT_TAIL(c); }
;                         } else {
;                             float binit[16];
; #pragma unroll
;                             for (int i = 0; i < 16; ++i) {
;                                 const int dist = qrow - (kp0 + crow(i, hh));
;                                 binit[i] = (dist < 0) ? -3e38f : (tab[dist > 255 ? 255 : dist] - mfix);
;                             }
; #pragma unroll
;                             for (int c = 0; c < NC; ++c) { ATT_QK(c, binit[i]); ATT_TAIL(c); }
;                         }
;                     } else {
;                         float binit[16];
;                         const LAS float* bl = (const LAS float*)(vtb + VT_BYTES) + 32 * kb2 + 4 * hh;
; #pragma unroll
;                         for (int g = 0; g < 4; ++g) {
;                             const f32x4 t = *(const LAS f32x4*)(bl + 8 * g);
; #pragma unroll
;                             for (int e = 0; e < 4; ++e) binit[4 * g + e] = (need_mask && (kp0 + crow(4 * g + e, hh) > qrow)) ? -3e38f : (t[e] - mfix);
;                         }
;                         ATT_QK(0, binit[i]); ATT_TAIL(0);
;                     }
;     ...
;                 }
; #pragma unroll
;                 for (int t2 = 0; t2 < 2; ++t2)
; #pragma unroll
;                     for (int d = 0; d < DV / 32; ++d) {
;                         const LAS unsigned char* vp = vtb + ((32 * kb2 + 16 * t2 + 4 * hh + ((lane & 15) >> 2)) * VPT + d * 32 + 16 * ((lane >> 4) & 1) + 4 * (lane & 3)) * 2;
;                         const s16x4 lo = vtr(vp), hi = vtr(vp + 8 * VPT * 2);
;                         const bf16x8 va = __builtin_shufflevector(lo, hi, 0, 1, 2, 3, 4, 5, 6, 7);
; #pragma unroll
;                         for (int c = 0; c < NC; ++c) O[c][d] = MFMA32(va, pb[c][t2], O[c][d]);
	v_mfma_f32_32x32x16_bf16 v[146:161], v[194:197], v[170:173], v[146:161]
	v_mul_f32_e32 v140, v138, v140
	v_cvt_pk_bf16_f32 v179, v139, v140
	v_lshlrev_b32_e32 v139, 16, v180
	v_and_b32_e32 v140, 0xffff0000, v180
	v_mul_f32_e32 v139, v138, v139
	v_mul_f32_e32 v140, v138, v140
	s_waitcnt lgkmcnt(4)
	v_mfma_f32_32x32x16_bf16 v[146:161], v[198:201], v[174:177], v[146:161]
	v_cvt_pk_bf16_f32 v180, v139, v140
	v_lshlrev_b32_e32 v139, 16, v181
	v_and_b32_e32 v140, 0xffff0000, v181
	v_mul_f32_e32 v139, v138, v139
	v_mul_f32_e32 v140, v138, v140
	v_cvt_pk_bf16_f32 v181, v139, v140
	v_add_u32_e32 v139, s2, v231
	ds_write_b128 v139, v[178:181]
	ds_read_b128 v[194:197], v243 offset:192
	ds_read_b128 v[198:201], v207 offset:6144
	s_waitcnt lgkmcnt(5)
	v_mfma_f32_32x32x16_bf16 v[130:145], v[202:205], v[214:217], 0
	ds_read_b128 v[202:205], v243 offset:224
	ds_read_b128 v[214:217], v207 offset:7168
	s_waitcnt lgkmcnt(5)
	v_mfma_f32_32x32x16_bf16 v[130:145], v[244:247], v[248:251], v[130:145]
	ds_read_b64_tr_b16 v[244:245], v218 offset:17408
	ds_read_b64_tr_b16 v[246:247], v218 offset:19968
	ds_read_b64_tr_b16 v[248:249], v218 offset:17472
	ds_read_b64_tr_b16 v[250:251], v218 offset:20032
	v_exp_f32_e32 v146, v146
	v_exp_f32_e32 v147, v147
	v_exp_f32_e32 v148, v148
	v_add_f32_e32 v220, v146, v147
	v_exp_f32_e32 v149, v149
	v_add_f32_e32 v220, v148, v220
	v_exp_f32_e32 v150, v150
	s_waitcnt lgkmcnt(6)
	v_mfma_f32_32x32x16_bf16 v[130:145], v[194:197], v[198:201], v[130:145]
	ds_read_b64_tr_b16 v[194:195], v218 offset:17536
	ds_read_b64_tr_b16 v[196:197], v218 offset:20096
	ds_read_b64_tr_b16 v[198:199], v218 offset:17600
	ds_read_b64_tr_b16 v[200:201], v218 offset:20160
	v_add_f32_e32 v220, v149, v220
	v_exp_f32_e32 v151, v151
	v_add_f32_e32 v220, v150, v220
	v_exp_f32_e32 v152, v152
	v_add_f32_e32 v220, v151, v220
	v_exp_f32_e32 v153, v153
	s_waitcnt lgkmcnt(8)
	v_mfma_f32_32x32x16_bf16 v[130:145], v[202:205], v[214:217], v[130:145]
	ds_read_b64_tr_b16 v[202:203], v219 offset:17408
	ds_read_b64_tr_b16 v[204:205], v219 offset:19968
	ds_read_b64_tr_b16 v[214:215], v219 offset:17472
	ds_read_b64_tr_b16 v[216:217], v219 offset:20032
	v_add_f32_e32 v220, v152, v220
	v_cvt_pk_bf16_f32 v146, v146, v147
	v_add_f32_e32 v220, v153, v220
	v_cvt_pk_bf16_f32 v147, v148, v149
	v_cvt_pk_bf16_f32 v148, v150, v151
	v_cvt_pk_bf16_f32 v149, v152, v153
	s_nop 1
	s_waitcnt lgkmcnt(10)
	v_mfma_f32_32x32x16_bf16 v[114:129], v[244:247], v[146:149], v[114:129]
	v_exp_f32_e32 v154, v154
	v_exp_f32_e32 v155, v155
	v_add_f32_e32 v220, v154, v220
	v_exp_f32_e32 v156, v156
	v_add_f32_e32 v220, v155, v220
	v_exp_f32_e32 v157, v157
	s_waitcnt lgkmcnt(8)
	v_mfma_f32_32x32x16_bf16 v[82:97], v[248:251], v[146:149], v[82:97]
	v_add_f32_e32 v220, v156, v220
	v_exp_f32_e32 v158, v158
	v_add_f32_e32 v220, v157, v220
	v_exp_f32_e32 v159, v159
	v_add_f32_e32 v220, v158, v220
	s_waitcnt lgkmcnt(6)
	v_mfma_f32_32x32x16_bf16 v[50:65], v[194:197], v[146:149], v[50:65]
	v_exp_f32_e32 v160, v160
	v_add_f32_e32 v220, v159, v220
	v_exp_f32_e32 v161, v161
	v_add_f32_e32 v220, v160, v220
	v_cvt_pk_bf16_f32 v150, v154, v155
	s_waitcnt lgkmcnt(4)
	v_mfma_f32_32x32x16_bf16 v[34:49], v[198:201], v[146:149], v[34:49]
	v_add_f32_e32 v220, v161, v220
	v_cvt_pk_bf16_f32 v151, v156, v157
	v_cvt_pk_bf16_f32 v152, v158, v159
	v_cvt_pk_bf16_f32 v153, v160, v161
	v_add_f32_e32 v209, v209, v220
	ds_read_b64_tr_b16 v[154:155], v219 offset:17536
	ds_read_b64_tr_b16 v[156:157], v219 offset:20096
	ds_read_b64_tr_b16 v[158:159], v219 offset:17600
	ds_read_b64_tr_b16 v[160:161], v219 offset:20160
	s_waitcnt lgkmcnt(6)
	v_mfma_f32_32x32x16_bf16 v[114:129], v[202:205], v[150:153], v[114:129]
	v_exp_f32_e32 v130, v130
	v_exp_f32_e32 v131, v131
	v_exp_f32_e32 v132, v132
	v_add_f32_e32 v213, v130, v131
	v_exp_f32_e32 v133, v133
	s_waitcnt lgkmcnt(4)
; #define LAS __attribute__((address_space(3)))
; #define MFMA32(a, b, c) __builtin_amdgcn_mfma_f32_32x32x16_bf16((a), (b), (c), 0, 0, 0)
; __device__ __forceinline__ s16x4 vtr(const LAS unsigned char* p) { return __builtin_bit_cast(s16x4, __builtin_amdgcn_ds_read_tr16_b64_v4i16((LAS v4i16_t*)p)); }
; template <int MODE>
; __device__ __forceinline__ void attn_item(const AttnP& p, int b, int h, int qb, LAS unsigned char* lds) {
;     ...
;                 for (int t2 = 0; t2 < 2; ++t2)
; #pragma unroll
;                     for (int d = 0; d < DV / 32; ++d) {
;                         const LAS unsigned char* vp = vtb + ((32 * kb2 + 16 * t2 + 4 * hh + ((lane & 15) >> 2)) * VPT + d * 32 + 16 * ((lane >> 4) & 1) + 4 * (lane & 3)) * 2;
;                         const s16x4 lo = vtr(vp), hi = vtr(vp + 8 * VPT * 2);
;                         const bf16x8 va = __builtin_shufflevector(lo, hi, 0, 1, 2, 3, 4, 5, 6, 7);
; #pragma unroll
;                         for (int c = 0; c < NC; ++c) O[c][d] = MFMA32(va, pb[c][t2], O[c][d]);
;                     }
	v_mfma_f32_32x32x16_bf16 v[82:97], v[214:217], v[150:153], v[82:97]
	v_add_f32_e32 v213, v132, v213
	v_exp_f32_e32 v134, v134
	v_add_f32_e32 v213, v133, v213
	v_exp_f32_e32 v135, v135
	v_add_f32_e32 v213, v134, v213
	s_waitcnt lgkmcnt(2)
	v_mfma_f32_32x32x16_bf16 v[50:65], v[154:157], v[150:153], v[50:65]
	v_exp_f32_e32 v136, v136
	v_add_f32_e32 v213, v135, v213
	v_exp_f32_e32 v137, v137
	v_add_f32_e32 v213, v136, v213
	v_cvt_pk_bf16_f32 v130, v130, v131
	s_waitcnt lgkmcnt(0)
	v_mfma_f32_32x32x16_bf16 v[34:49], v[158:161], v[150:153], v[34:49]
	v_add_f32_e32 v213, v137, v213
	v_cvt_pk_bf16_f32 v131, v132, v133
	v_cvt_pk_bf16_f32 v132, v134, v135
	v_cvt_pk_bf16_f32 v133, v136, v137
	s_nop 1
	v_mfma_f32_32x32x16_bf16 v[98:113], v[244:247], v[130:133], v[98:113]
	v_exp_f32_e32 v138, v138
	v_exp_f32_e32 v139, v139
	v_add_f32_e32 v213, v138, v213
	v_exp_f32_e32 v140, v140
	v_add_f32_e32 v213, v139, v213
	v_exp_f32_e32 v141, v141
	v_mfma_f32_32x32x16_bf16 v[66:81], v[248:251], v[130:133], v[66:81]
	v_add_f32_e32 v213, v140, v213
	v_exp_f32_e32 v142, v142
	v_add_f32_e32 v213, v141, v213
	v_exp_f32_e32 v143, v143
	v_add_f32_e32 v213, v142, v213
	v_mfma_f32_32x32x16_bf16 v[18:33], v[194:197], v[130:133], v[18:33]
	v_exp_f32_e32 v144, v144
	v_add_f32_e32 v213, v143, v213
	v_exp_f32_e32 v145, v145
	v_add_f32_e32 v213, v144, v213
	v_cvt_pk_bf16_f32 v134, v138, v139
	v_mfma_f32_32x32x16_bf16 v[2:17], v[198:201], v[130:133], v[2:17]
	v_add_f32_e32 v213, v145, v213
	v_cvt_pk_bf16_f32 v135, v140, v141
	v_cvt_pk_bf16_f32 v136, v142, v143
	v_cvt_pk_bf16_f32 v137, v144, v145
	v_add_f32_e32 v208, v208, v213
	s_nop 1
	v_mfma_f32_32x32x16_bf16 v[98:113], v[202:205], v[134:137], v[98:113]
	s_waitcnt vmcnt(2)
	v_and_b32_e32 v138, 0xffff0000, v185
	v_lshlrev_b32_e32 v142, 16, v185
	v_mul_f32_e32 v138, v138, v138
	v_fmac_f32_e32 v138, v142, v142
	v_and_b32_e32 v139, 0xffff0000, v184
	v_mfma_f32_32x32x16_bf16 v[66:81], v[214:217], v[134:137], v[66:81]
	v_lshlrev_b32_e32 v142, 16, v184
	v_mul_f32_e32 v139, v139, v139
	v_fmac_f32_e32 v139, v142, v142
	v_and_b32_e32 v140, 0xffff0000, v182
	v_lshlrev_b32_e32 v142, 16, v182
	v_mul_f32_e32 v140, v140, v140
	v_mfma_f32_32x32x16_bf16 v[18:33], v[154:157], v[134:137], v[18:33]
	v_fmac_f32_e32 v140, v142, v142
	v_and_b32_e32 v141, 0xffff0000, v183
	v_lshlrev_b32_e32 v142, 16, v183
	v_mul_f32_e32 v141, v141, v141
	v_fmac_f32_e32 v141, v142, v142
	v_add_f32_e32 v140, v140, v141
	v_mfma_f32_32x32x16_bf16 v[2:17], v[158:161], v[134:137], v[2:17]
	v_add_f32_e32 v139, v139, v140
	v_add_f32_e32 v138, v138, v139
	s_nop 1
	v_add_f32_dpp v138, v138, v138 quad_perm:[1,0,3,2] row_mask:0xf bank_mask:0xf bound_ctrl:1
	s_nop 1
	v_add_f32_dpp v138, v138, v138 quad_perm:[2,3,0,1] row_mask:0xf bank_mask:0xf bound_ctrl:1
	s_nop 1
	v_add_f32_dpp v138, v138, v138 row_half_mirror row_mask:0xf bank_mask:0xf bound_ctrl:1
	v_fmamk_f32 v138, v138, 0x3c800000, v211
	v_rsq_f32_e32 v138, v138
	v_lshlrev_b32_e32 v139, 16, v182
	v_and_b32_e32 v140, 0xffff0000, v182
	v_mul_f32_e32 v139, v138, v139
	v_mul_f32_e32 v140, v138, v140
	v_cvt_pk_bf16_f32 v182, v139, v140
	v_lshlrev_b32_e32 v139, 16, v183
	v_and_b32_e32 v140, 0xffff0000, v183
	v_mul_f32_e32 v139, v138, v139
	v_mul_f32_e32 v140, v138, v140
	v_cvt_pk_bf16_f32 v183, v139, v140
	v_lshlrev_b32_e32 v139, 16, v184
	v_and_b32_e32 v140, 0xffff0000, v184
	v_mul_f32_e32 v139, v138, v139
	v_mul_f32_e32 v140, v138, v140
	v_cvt_pk_bf16_f32 v184, v139, v140
	v_lshlrev_b32_e32 v139, 16, v185
	v_and_b32_e32 v140, 0xffff0000, v185
	v_mul_f32_e32 v139, v138, v139
	v_mul_f32_e32 v140, v138, v140
	v_cvt_pk_bf16_f32 v185, v139, v140
	v_add_u32_e32 v139, s2, v233
	ds_write_b128 v139, v[182:185]
	s_waitcnt vmcnt(1)
	v_add_u32_e32 v143, s2, v232
	ds_write_b128 v143, v[186:189] offset:17408
	s_waitcnt vmcnt(0)
	v_add_u32_e32 v144, s2, v234
	ds_write_b128 v144, v[190:193] offset:17408
	s_branch .LBB0_495
	.p2align 6
